# RG-LRU: the two fully serialized gate-MFMA clusters (sub-block 2 of each direction) software-pipelined with a second B-fragment set v[224:231]
# baseline (speedup 1.0000x reference)
.LBB0_272:
	s_or_b64 exec, exec, s[8:9]
	s_setprio 1
	ds_read_b128 v[0:3], v145 offset:24576
	ds_read_b128 v[4:7], v145 offset:57344
	ds_read_b128 v[224:227], v147 offset:24576
	ds_read_b128 v[228:231], v147 offset:57344
	s_waitcnt lgkmcnt(3)
	v_mfma_f32_32x32x16_bf16 v[32:47], v[48:51], v[0:3], 0
	s_waitcnt lgkmcnt(2)
	v_mfma_f32_32x32x16_bf16 v[16:31], v[48:51], v[4:7], 0
	ds_read_b128 v[0:3], v142 offset:24576
	ds_read_b128 v[4:7], v142 offset:57344
	s_waitcnt lgkmcnt(3)
	v_mfma_f32_32x32x16_bf16 v[32:47], v[52:55], v[224:227], v[32:47]
	s_waitcnt lgkmcnt(2)
	v_mfma_f32_32x32x16_bf16 v[16:31], v[52:55], v[228:231], v[16:31]
	ds_read_b128 v[224:227], v146 offset:24576
	ds_read_b128 v[228:231], v146 offset:57344
	s_waitcnt lgkmcnt(3)
	v_mfma_f32_32x32x16_bf16 v[32:47], v[56:59], v[0:3], v[32:47]
	s_waitcnt lgkmcnt(2)
	v_mfma_f32_32x32x16_bf16 v[16:31], v[56:59], v[4:7], v[16:31]
	ds_read_b128 v[0:3], v141 offset:24576
	ds_read_b128 v[4:7], v141 offset:57344
	s_waitcnt lgkmcnt(3)
	v_mfma_f32_32x32x16_bf16 v[32:47], v[60:63], v[224:227], v[32:47]
	s_waitcnt lgkmcnt(2)
	v_mfma_f32_32x32x16_bf16 v[16:31], v[60:63], v[228:231], v[16:31]
	ds_read_b128 v[224:227], v144 offset:24576
	ds_read_b128 v[228:231], v144 offset:57344
	s_waitcnt lgkmcnt(3)
	v_mfma_f32_32x32x16_bf16 v[32:47], v[64:67], v[0:3], v[32:47]
	s_waitcnt lgkmcnt(2)
	v_mfma_f32_32x32x16_bf16 v[16:31], v[64:67], v[4:7], v[16:31]
	ds_read_b128 v[0:3], v139 offset:24576
	ds_read_b128 v[4:7], v139 offset:57344
	s_waitcnt lgkmcnt(3)
	v_mfma_f32_32x32x16_bf16 v[32:47], v[68:71], v[224:227], v[32:47]
	s_waitcnt lgkmcnt(2)
	v_mfma_f32_32x32x16_bf16 v[16:31], v[68:71], v[228:231], v[16:31]
	ds_read_b128 v[224:227], v143 offset:24576
	ds_read_b128 v[228:231], v143 offset:57344
	s_waitcnt lgkmcnt(3)
	v_mfma_f32_32x32x16_bf16 v[32:47], v[72:75], v[0:3], v[32:47]
	s_waitcnt lgkmcnt(2)
	v_mfma_f32_32x32x16_bf16 v[16:31], v[72:75], v[4:7], v[16:31]
	s_waitcnt lgkmcnt(1)
	v_mfma_f32_32x32x16_bf16 v[32:47], v[76:79], v[224:227], v[32:47]
	s_waitcnt lgkmcnt(0)
	v_mfma_f32_32x32x16_bf16 v[16:31], v[76:79], v[228:231], v[16:31]
	v_mfma_f32_32x32x16_bf16 v[0:15], v[56:59], v[80:83], 0
	v_mfma_f32_32x32x16_bf16 v[0:15], v[60:63], v[84:87], v[0:15]
	s_setprio 0
	v_lshl_or_b32 v93, v138, 2, v133
	s_waitcnt vmcnt(16)
	ds_read_b32 v251, v167 offset:128
	v_mul_f32_e32 v148, 0xbfb8aa3b, v173
	v_mul_f32_e32 v93, 0xbfb8aa3b, v174
	v_fmamk_f32 v32, v32, 0xbfb8aa3b, v148
	v_fmamk_f32 v16, v16, 0xbfb8aa3b, v93
	v_exp_f32_e32 v32, v32
	v_exp_f32_e32 v150, v16
	v_fmamk_f32 v17, v17, 0xbfb8aa3b, v93
	v_exp_f32_e32 v151, v17
	v_add_f32_e32 v32, 1.0, v32
	v_add_f32_e32 v150, 1.0, v150
	v_rcp_f32_e32 v17, v32
	v_rcp_f32_e32 v32, v150
	v_fmamk_f32 v33, v33, 0xbfb8aa3b, v148
	v_fmamk_f32 v34, v34, 0xbfb8aa3b, v148
	v_exp_f32_e32 v33, v33
	v_exp_f32_e32 v34, v34
	v_add_f32_e32 v33, 1.0, v33
	v_add_f32_e32 v34, 1.0, v34
	v_rcp_f32_e32 v33, v33
	v_rcp_f32_e32 v34, v34
	v_fmamk_f32 v18, v18, 0xbfb8aa3b, v93
	v_fmamk_f32 v19, v19, 0xbfb8aa3b, v93
	v_exp_f32_e32 v18, v18
	s_waitcnt lgkmcnt(0)
	v_mul_f32_e32 v149, 0x3fb8aa3b, v251
	v_mul_f32_e32 v16, v17, v149
	v_mul_f32_e32 v17, v33, v149
	v_exp_f32_e32 v33, v16
	v_mul_f32_e32 v16, v34, v149
	v_exp_f32_e32 v152, v16
	v_fmamk_f32 v16, v35, 0xbfb8aa3b, v148
	v_exp_f32_e32 v16, v16
	v_exp_f32_e32 v150, v17
	v_add_f32_e32 v16, 1.0, v16
	v_rcp_f32_e32 v16, v16
	v_exp_f32_e32 v19, v19
	v_add_f32_e32 v151, 1.0, v151
	v_add_f32_e32 v18, 1.0, v18
	v_mul_f32_e32 v16, v16, v149
	v_exp_f32_e32 v16, v16
	v_fma_f32 v35, -v152, v152, 1.0
	v_rcp_f32_e32 v17, v151
	v_fma_f32 v34, -v33, v33, 1.0
	v_fma_f32 v151, -v150, v150, 1.0
	v_rcp_f32_e32 v18, v18
	v_sqrt_f32_e32 v35, v35
	v_add_f32_e32 v19, 1.0, v19
	v_fma_f32 v153, -v16, v16, 1.0
	v_sqrt_f32_e32 v34, v34
	v_sqrt_f32_e32 v151, v151
	v_rcp_f32_e32 v19, v19
	v_sqrt_f32_e32 v153, v153
	v_mul_f32_e32 v35, v18, v35
	v_fmamk_f32 v18, v36, 0xbfb8aa3b, v148
	v_mul_f32_e32 v32, v32, v34
	v_mul_f32_e32 v34, v17, v151
	v_mul_f32_e32 v17, v19, v153
	v_fmamk_f32 v19, v20, 0xbfb8aa3b, v93
	v_exp_f32_e32 v18, v18
	v_exp_f32_e32 v19, v19
	v_mul_f32_e32 v3, v3, v17
	v_add_f32_e32 v17, 1.0, v18
	v_rcp_f32_e32 v17, v17
	v_add_f32_e32 v18, 1.0, v19
	v_fmamk_f32 v19, v37, 0xbfb8aa3b, v148
	v_exp_f32_e32 v19, v19
	v_mul_f32_e32 v17, v17, v149
	v_exp_f32_e32 v36, v17
	v_add_f32_e32 v17, 1.0, v19
	v_rcp_f32_e32 v17, v17
	v_fmamk_f32 v19, v21, 0xbfb8aa3b, v93
	v_exp_f32_e32 v19, v19
	v_mul_f32_e32 v17, v17, v149
	v_exp_f32_e32 v37, v17
	v_fmamk_f32 v17, v38, 0xbfb8aa3b, v148
	v_exp_f32_e32 v17, v17
	v_fmamk_f32 v23, v23, 0xbfb8aa3b, v93
	v_add_f32_e32 v19, 1.0, v19
	v_fma_f32 v21, -v37, v37, 1.0
	v_add_f32_e32 v17, 1.0, v17
	v_rcp_f32_e32 v17, v17
	v_fma_f32 v20, -v36, v36, 1.0
	v_rcp_f32_e32 v19, v19
	v_mul_f32_e32 v17, v17, v149
	v_exp_f32_e32 v38, v17
	v_fmamk_f32 v17, v39, 0xbfb8aa3b, v148
	v_exp_f32_e32 v17, v17
	v_sqrt_f32_e32 v21, v21
	v_exp_f32_e32 v23, v23
	v_rcp_f32_e32 v18, v18
	v_add_f32_e32 v17, 1.0, v17
	v_rcp_f32_e32 v17, v17
	v_sqrt_f32_e32 v20, v20
	v_add_f32_e32 v23, 1.0, v23
	v_mul_f32_e32 v154, v19, v21
	v_mul_f32_e32 v17, v17, v149
	v_exp_f32_e32 v17, v17
	v_fmamk_f32 v19, v40, 0xbfb8aa3b, v148
	v_rcp_f32_e32 v23, v23
	v_mul_f32_e32 v153, v18, v20
	v_fma_f32 v151, -v17, v17, 1.0
	v_sqrt_f32_e32 v151, v151
	v_fmamk_f32 v20, v24, 0xbfb8aa3b, v93
	v_fmamk_f32 v22, v22, 0xbfb8aa3b, v93
	v_exp_f32_e32 v19, v19
	v_exp_f32_e32 v20, v20
	v_exp_f32_e32 v22, v22
	v_mul_f32_e32 v18, v23, v151
	v_mul_f32_e32 v7, v7, v18
	v_add_f32_e32 v18, 1.0, v19
	v_rcp_f32_e32 v18, v18
	v_add_f32_e32 v19, 1.0, v20
	v_fmamk_f32 v20, v41, 0xbfb8aa3b, v148
	v_add_f32_e32 v22, 1.0, v22
	v_fma_f32 v39, -v38, v38, 1.0
	v_rcp_f32_e32 v22, v22
	v_sqrt_f32_e32 v39, v39
	v_exp_f32_e32 v20, v20
	v_mul_f32_e32 v18, v18, v149
	v_mul_f32_e32 v21, v22, v39
	v_exp_f32_e32 v39, v18
	v_add_f32_e32 v18, 1.0, v20
	v_rcp_f32_e32 v18, v18
	v_fmamk_f32 v20, v25, 0xbfb8aa3b, v93
	v_exp_f32_e32 v20, v20
	v_mul_f32_e32 v18, v18, v149
	v_exp_f32_e32 v40, v18
	v_fmamk_f32 v18, v42, 0xbfb8aa3b, v148
	v_exp_f32_e32 v18, v18
	v_fmamk_f32 v24, v26, 0xbfb8aa3b, v93
	v_fmamk_f32 v26, v27, 0xbfb8aa3b, v93
	v_add_f32_e32 v20, 1.0, v20
	v_add_f32_e32 v18, 1.0, v18
	v_rcp_f32_e32 v18, v18
	v_fma_f32 v23, -v40, v40, 1.0
	v_fma_f32 v22, -v39, v39, 1.0
	v_mul_f32_e32 v18, v18, v149
	v_exp_f32_e32 v41, v18
	v_fmamk_f32 v18, v43, 0xbfb8aa3b, v148
	v_exp_f32_e32 v18, v18
	v_rcp_f32_e32 v20, v20
	v_sqrt_f32_e32 v23, v23
	v_exp_f32_e32 v26, v26
	v_add_f32_e32 v18, 1.0, v18
	v_rcp_f32_e32 v18, v18
	v_rcp_f32_e32 v19, v19
	v_sqrt_f32_e32 v22, v22
	v_add_f32_e32 v26, 1.0, v26
	v_mul_f32_e32 v18, v18, v149
	v_exp_f32_e32 v18, v18
	v_mul_f32_e32 v43, v20, v23
	v_fmamk_f32 v20, v44, 0xbfb8aa3b, v148
	v_rcp_f32_e32 v26, v26
	v_fma_f32 v27, -v18, v18, 1.0
	v_sqrt_f32_e32 v27, v27
	v_mul_f32_e32 v42, v19, v22
	v_fmamk_f32 v22, v28, 0xbfb8aa3b, v93
	v_exp_f32_e32 v20, v20
	v_exp_f32_e32 v22, v22
	v_mul_f32_e32 v19, v26, v27
	v_mul_f32_e32 v11, v11, v19
	v_add_f32_e32 v19, 1.0, v20
	v_rcp_f32_e32 v19, v19
	v_add_f32_e32 v20, 1.0, v22
	v_fmamk_f32 v22, v45, 0xbfb8aa3b, v148
	v_exp_f32_e32 v22, v22
	v_mul_f32_e32 v19, v19, v149
	v_exp_f32_e32 v44, v19
	v_add_f32_e32 v19, 1.0, v22
	v_rcp_f32_e32 v19, v19
	v_exp_f32_e32 v24, v24
	v_fmamk_f32 v22, v29, 0xbfb8aa3b, v93
	v_mul_f32_e32 v19, v19, v149
	v_exp_f32_e32 v45, v19
	v_fmamk_f32 v19, v46, 0xbfb8aa3b, v148
	v_exp_f32_e32 v19, v19
	v_add_f32_e32 v24, 1.0, v24
	v_fma_f32 v25, -v41, v41, 1.0
	v_add_f32_e32 v19, 1.0, v19
	v_rcp_f32_e32 v19, v19
	v_exp_f32_e32 v22, v22
	v_rcp_f32_e32 v24, v24
	v_sqrt_f32_e32 v25, v25
	v_mul_f32_e32 v19, v19, v149
	v_exp_f32_e32 v46, v19
	v_fmamk_f32 v19, v47, 0xbfb8aa3b, v148
	v_add_f32_e32 v22, 1.0, v22
	v_exp_f32_e32 v19, v19
	v_mul_f32_e32 v151, v24, v25
	v_rcp_f32_e32 v24, v22
	v_fma_f32 v22, -v45, v45, 1.0
	v_sqrt_f32_e32 v25, v22
	v_fmamk_f32 v22, v30, 0xbfb8aa3b, v93
	v_exp_f32_e32 v22, v22
	v_add_f32_e32 v19, 1.0, v19
	v_rcp_f32_e32 v19, v19
	v_fma_f32 v27, -v46, v46, 1.0
	v_add_f32_e32 v22, 1.0, v22
	v_rcp_f32_e32 v26, v22
	v_fmamk_f32 v22, v31, 0xbfb8aa3b, v93
	v_mul_f32_e32 v19, v19, v149
	v_exp_f32_e32 v28, v22
	v_exp_f32_e32 v22, v19
	v_sqrt_f32_e32 v19, v27
	v_fma_f32 v23, -v44, v44, 1.0
	v_add_f32_e32 v27, 1.0, v28
	v_fma_f32 v28, -v22, v22, 1.0
	v_rcp_f32_e32 v27, v27
	v_sqrt_f32_e32 v28, v28
	v_rcp_f32_e32 v20, v20
	v_sqrt_f32_e32 v23, v23
	v_mul_f32_e32 v148, v26, v19
	v_mul_f32_e32 v19, v27, v28
	v_fmac_f32_e32 v7, 0, v17
	v_mul_f32_e32 v15, v15, v19
	v_mul_f32_e32 v19, v38, v7
	v_fmac_f32_e32 v19, v6, v21
	v_fmac_f32_e32 v3, 0, v16
	v_mul_f32_e32 v21, v37, v19
	v_mul_f32_e32 v47, v20, v23
	v_mul_f32_e32 v20, v152, v3
	v_fmac_f32_e32 v21, v5, v154
	v_fmac_f32_e32 v15, 0, v22
	v_mul_f32_e32 v93, v24, v25
	v_fmac_f32_e32 v20, v2, v35
	v_mul_f32_e32 v24, v36, v21
	v_fmac_f32_e32 v11, 0, v18
	v_mul_f32_e32 v2, v46, v15
	v_fmac_f32_e32 v24, v4, v153
	v_mul_f32_e32 v4, v41, v11
	v_fmac_f32_e32 v2, v14, v148
	v_fmac_f32_e32 v4, v10, v151
	v_mul_f32_e32 v5, v45, v2
	v_mul_f32_e32 v23, v150, v20
	v_mul_f32_e32 v6, v40, v4
	v_fmac_f32_e32 v5, v13, v93
	v_fmac_f32_e32 v23, v1, v34
	v_fmac_f32_e32 v6, v9, v43
	v_mul_f32_e32 v14, v22, v46
	v_mul_f32_e32 v9, v44, v5
	v_mul_f32_e32 v25, v33, v23
	v_mul_f32_e32 v13, v45, v14
	v_fmac_f32_e32 v9, v12, v47
	v_fmac_f32_e32 v25, v0, v32
	v_mul_f32_e32 v12, v44, v13
	ds_bpermute_b32 v0, v137, v9
	ds_bpermute_b32 v35, v137, v12
	v_mul_f32_e32 v28, v18, v41
	v_mul_f32_e32 v26, v16, v152
	v_mul_f32_e32 v27, v17, v38
	v_mul_f32_e32 v31, v40, v28
	v_mul_f32_e32 v10, v39, v6
	v_mul_f32_e32 v29, v150, v26
	v_mul_f32_e32 v30, v37, v27
	v_fmac_f32_e32 v10, v8, v42
	v_mul_f32_e32 v34, v39, v31
	v_mul_f32_e32 v32, v33, v29
	v_mul_f32_e32 v33, v36, v30
	s_waitcnt lgkmcnt(1)
	v_cndmask_b32_e64 v36, v0, v9, s[4:5]
	v_cndmask_b32_e64 v37, v9, v0, s[4:5]
	ds_bpermute_b32 v0, v137, v34
	ds_bpermute_b32 v40, v137, v10
	s_waitcnt lgkmcnt(2)
	v_cndmask_b32_e64 v8, v12, v35, s[4:5]
	v_fmac_f32_e32 v37, 0, v8
	ds_bpermute_b32 v8, v137, v33
	v_cndmask_b32_e64 v1, v35, v12, s[4:5]
	v_mul_f32_e32 v38, v12, v35
	v_fmac_f32_e32 v36, v1, v37
	s_waitcnt lgkmcnt(2)
	v_cndmask_b32_e64 v1, v0, v34, s[4:5]
	s_waitcnt lgkmcnt(1)
	v_cndmask_b32_e64 v39, v40, v10, s[4:5]
	v_cndmask_b32_e64 v0, v34, v0, s[4:5]
	v_cndmask_b32_e64 v40, v10, v40, s[4:5]
	ds_bpermute_b32 v44, v137, v24
	v_mul_f32_e32 v41, v38, v0
	v_fmac_f32_e32 v40, v0, v36
	v_mul_f32_e32 v42, v1, v41
	v_fmac_f32_e32 v39, v1, v40
	s_waitcnt lgkmcnt(1)
	v_cndmask_b32_e64 v0, v8, v33, s[4:5]
	v_cndmask_b32_e64 v1, v33, v8, s[4:5]
	ds_bpermute_b32 v8, v137, v32
	ds_bpermute_b32 v47, v137, v25
	s_waitcnt lgkmcnt(2)
	v_cndmask_b32_e64 v43, v44, v24, s[4:5]
	v_cndmask_b32_e64 v44, v24, v44, s[4:5]
	v_mul_f32_e32 v45, v1, v42
	v_fmac_f32_e32 v44, v1, v39
	v_mul_f32_e32 v46, v0, v45
	v_fmac_f32_e32 v43, v0, v44
	s_waitcnt lgkmcnt(1)
	v_cndmask_b32_e64 v0, v32, v8, s[4:5]
	s_waitcnt lgkmcnt(0)
	v_cndmask_b32_e64 v47, v25, v47, s[4:5]
	v_mul_f32_e32 v93, v0, v46
	v_fmac_f32_e32 v47, v0, v43
	s_and_saveexec_b64 s[8:9], s[4:5]
	v_mul_f32_e32 v0, v32, v93
	v_fma_f32 v1, v32, v47, v25
	ds_write_b64 v136, v[0:1] offset:2048
	s_or_b64 exec, exec, s[8:9]
	v_cndmask_b32_e64 v0, 0, 1, s[14:15]
	v_cmp_ne_u32_e64 s[8:9], 1, v0
	s_andn2_b64 vcc, exec, s[14:15]
	s_waitcnt lgkmcnt(0)
	s_barrier
	s_cbranch_vccnz .LBB0_277
	v_add3_u32 v148, v140, v91, s93
	v_mov_b32_e32 v8, 1.0
	v_mov_b32_e32 v1, 0
	s_mov_b32 s12, 7

.LBB0_333:
	s_or_b64 exec, exec, s[6:7]
	s_setprio 1
	ds_read_b128 v[0:3], v148 offset:24576
	ds_read_b128 v[4:7], v148 offset:57344
	ds_read_b128 v[224:227], v150 offset:24576
	ds_read_b128 v[228:231], v150 offset:57344
	s_waitcnt lgkmcnt(3)
	v_mfma_f32_32x32x16_bf16 v[32:47], v[48:51], v[0:3], 0
	s_waitcnt lgkmcnt(2)
	v_mfma_f32_32x32x16_bf16 v[16:31], v[48:51], v[4:7], 0
	ds_read_b128 v[0:3], v145 offset:24576
	ds_read_b128 v[4:7], v145 offset:57344
	s_waitcnt lgkmcnt(3)
	v_mfma_f32_32x32x16_bf16 v[32:47], v[52:55], v[224:227], v[32:47]
	s_waitcnt lgkmcnt(2)
	v_mfma_f32_32x32x16_bf16 v[16:31], v[52:55], v[228:231], v[16:31]
	ds_read_b128 v[224:227], v149 offset:24576
	ds_read_b128 v[228:231], v149 offset:57344
	s_waitcnt lgkmcnt(3)
	v_mfma_f32_32x32x16_bf16 v[32:47], v[56:59], v[0:3], v[32:47]
	s_waitcnt lgkmcnt(2)
	v_mfma_f32_32x32x16_bf16 v[16:31], v[56:59], v[4:7], v[16:31]
	ds_read_b128 v[0:3], v144 offset:24576
	ds_read_b128 v[4:7], v144 offset:57344
	s_waitcnt lgkmcnt(3)
	v_mfma_f32_32x32x16_bf16 v[32:47], v[60:63], v[224:227], v[32:47]
	s_waitcnt lgkmcnt(2)
	v_mfma_f32_32x32x16_bf16 v[16:31], v[60:63], v[228:231], v[16:31]
	ds_read_b128 v[224:227], v147 offset:24576
	ds_read_b128 v[228:231], v147 offset:57344
	s_waitcnt lgkmcnt(3)
	v_mfma_f32_32x32x16_bf16 v[32:47], v[64:67], v[0:3], v[32:47]
	s_waitcnt lgkmcnt(2)
	v_mfma_f32_32x32x16_bf16 v[16:31], v[64:67], v[4:7], v[16:31]
	ds_read_b128 v[0:3], v143 offset:24576
	ds_read_b128 v[4:7], v143 offset:57344
	s_waitcnt lgkmcnt(3)
	v_mfma_f32_32x32x16_bf16 v[32:47], v[68:71], v[224:227], v[32:47]
	s_waitcnt lgkmcnt(2)
	v_mfma_f32_32x32x16_bf16 v[16:31], v[68:71], v[228:231], v[16:31]
	ds_read_b128 v[224:227], v146 offset:24576
	ds_read_b128 v[228:231], v146 offset:57344
	s_waitcnt lgkmcnt(3)
	v_mfma_f32_32x32x16_bf16 v[32:47], v[72:75], v[0:3], v[32:47]
	s_waitcnt lgkmcnt(2)
	v_mfma_f32_32x32x16_bf16 v[16:31], v[72:75], v[4:7], v[16:31]
	s_waitcnt lgkmcnt(1)
	v_mfma_f32_32x32x16_bf16 v[32:47], v[76:79], v[224:227], v[32:47]
	s_waitcnt lgkmcnt(0)
	v_mfma_f32_32x32x16_bf16 v[16:31], v[76:79], v[228:231], v[16:31]
	v_mfma_f32_32x32x16_bf16 v[0:15], v[56:59], v[80:83], 0
	v_mfma_f32_32x32x16_bf16 v[0:15], v[60:63], v[84:87], v[0:15]
	s_setprio 0
	s_waitcnt vmcnt(16)
	ds_read_b32 v251, v167 offset:128
	v_mul_f32_e32 v151, 0xbfb8aa3b, v173
	v_mul_f32_e32 v93, 0xbfb8aa3b, v174
	v_fmamk_f32 v32, v32, 0xbfb8aa3b, v151
	v_fmamk_f32 v34, v34, 0xbfb8aa3b, v151
	v_fmamk_f32 v33, v33, 0xbfb8aa3b, v151
	v_fmamk_f32 v35, v35, 0xbfb8aa3b, v151
	v_fmamk_f32 v16, v16, 0xbfb8aa3b, v93
	v_fmamk_f32 v17, v17, 0xbfb8aa3b, v93
	v_exp_f32_e32 v32, v32
	v_exp_f32_e32 v34, v34
	v_exp_f32_e32 v33, v33
	v_exp_f32_e32 v161, v35
	v_exp_f32_e32 v91, v16
	v_exp_f32_e32 v152, v17
	v_add_f32_e32 v32, 1.0, v32
	v_add_f32_e32 v162, 1.0, v34
	v_add_f32_e32 v33, 1.0, v33
	v_rcp_f32_e32 v163, v32
	v_rcp_f32_e32 v165, v33
	v_add_f32_e32 v91, 1.0, v91
	v_rcp_f32_e32 v164, v91
	v_add_f32_e32 v152, 1.0, v152
	v_rcp_f32_e32 v166, v152
	v_fmamk_f32 v18, v18, 0xbfb8aa3b, v93
	v_exp_f32_e32 v18, v18
	v_fmamk_f32 v20, v20, 0xbfb8aa3b, v93
	v_add_f32_e32 v18, 1.0, v18
	v_exp_f32_e32 v20, v20
	v_fmamk_f32 v19, v19, 0xbfb8aa3b, v93
	v_exp_f32_e32 v19, v19
	v_fmamk_f32 v21, v21, 0xbfb8aa3b, v93
	s_waitcnt lgkmcnt(0)
	v_mul_f32_e32 v33, 0x3fb8aa3b, v251
	v_mul_f32_e32 v16, v163, v33
	v_exp_f32_e32 v32, v16
	v_mul_f32_e32 v17, v165, v33
	v_exp_f32_e32 v34, v17
	v_rcp_f32_e32 v16, v162
	v_rcp_f32_e32 v17, v18
	v_fma_f32 v18, -v32, v32, 1.0
	v_sqrt_f32_e32 v18, v18
	v_mul_f32_e32 v16, v16, v33
	v_add_f32_e32 v19, 1.0, v19
	v_mul_f32_e32 v18, v164, v18
	v_mul_f32_e32 v18, v0, v18
	v_exp_f32_e32 v0, v16
	v_add_f32_e32 v16, 1.0, v161
	v_rcp_f32_e32 v16, v16
	v_rcp_f32_e32 v19, v19
	v_fma_f32 v91, -v0, v0, 1.0
	v_sqrt_f32_e32 v91, v91
	v_mul_f32_e32 v16, v16, v33
	v_exp_f32_e32 v152, v16
	v_fmamk_f32 v16, v36, 0xbfb8aa3b, v151
	v_exp_f32_e32 v16, v16
	v_mul_f32_e32 v91, v17, v91
	v_add_f32_e32 v17, 1.0, v20
	v_fma_f32 v36, -v152, v152, 1.0
	v_add_f32_e32 v16, 1.0, v16
	v_rcp_f32_e32 v16, v16
	v_sqrt_f32_e32 v36, v36
	v_rcp_f32_e32 v17, v17
	v_mul_f32_e32 v16, v16, v33
	v_exp_f32_e32 v20, v16
	v_fmamk_f32 v16, v37, 0xbfb8aa3b, v151
	v_exp_f32_e32 v16, v16
	v_mul_f32_e32 v36, v19, v36
	v_fma_f32 v19, -v20, v20, 1.0
	v_sqrt_f32_e32 v19, v19
	v_add_f32_e32 v16, 1.0, v16
	v_rcp_f32_e32 v16, v16
	v_exp_f32_e32 v21, v21
	v_mul_f32_e32 v17, v17, v19
	v_mul_f32_e32 v19, v4, v17
	v_mul_f32_e32 v16, v16, v33
	v_exp_f32_e32 v37, v16
	v_fmamk_f32 v16, v38, 0xbfb8aa3b, v151
	v_exp_f32_e32 v16, v16
	v_add_f32_e32 v4, 1.0, v21
	v_fmamk_f32 v21, v22, 0xbfb8aa3b, v93
	v_add_f32_e32 v16, 1.0, v16
	v_rcp_f32_e32 v16, v16
	v_fma_f32 v17, -v37, v37, 1.0
	v_exp_f32_e32 v21, v21
	v_rcp_f32_e32 v4, v4
	v_mul_f32_e32 v16, v16, v33
	v_sqrt_f32_e32 v17, v17
	v_exp_f32_e32 v38, v16
	v_add_f32_e32 v16, 1.0, v21
	v_fmamk_f32 v21, v39, 0xbfb8aa3b, v151
	v_mul_f32_e32 v4, v4, v17
	v_fma_f32 v17, -v38, v38, 1.0
	v_rcp_f32_e32 v16, v16
	v_sqrt_f32_e32 v17, v17
	v_exp_f32_e32 v21, v21
	v_fmamk_f32 v22, v23, 0xbfb8aa3b, v93
	v_mul_f32_e32 v23, v16, v17
	v_add_f32_e32 v16, 1.0, v21
	v_rcp_f32_e32 v16, v16
	v_fmamk_f32 v21, v40, 0xbfb8aa3b, v151
	v_exp_f32_e32 v21, v21
	v_mul_f32_e32 v16, v16, v33
	v_exp_f32_e32 v39, v16
	v_add_f32_e32 v16, 1.0, v21
	v_rcp_f32_e32 v16, v16
	v_exp_f32_e32 v22, v22
	v_fmamk_f32 v21, v24, 0xbfb8aa3b, v93
	v_mul_f32_e32 v16, v16, v33
	v_add_f32_e32 v17, 1.0, v22
	v_fma_f32 v22, -v39, v39, 1.0
	v_sqrt_f32_e32 v24, v22
	v_exp_f32_e32 v22, v16
	v_fmamk_f32 v16, v41, 0xbfb8aa3b, v151
	v_exp_f32_e32 v16, v16
	v_exp_f32_e32 v21, v21
	v_fma_f32 v40, -v22, v22, 1.0
	v_rcp_f32_e32 v17, v17
	v_add_f32_e32 v16, 1.0, v16
	v_rcp_f32_e32 v16, v16
	v_add_f32_e32 v21, 1.0, v21
	v_rcp_f32_e32 v21, v21
	v_sqrt_f32_e32 v40, v40
	v_mul_f32_e32 v16, v16, v33
	v_mul_f32_e32 v24, v17, v24
	v_mul_f32_e32 v17, v21, v40
	v_exp_f32_e32 v40, v16
	v_fmamk_f32 v16, v42, 0xbfb8aa3b, v151
	v_fmamk_f32 v25, v25, 0xbfb8aa3b, v93
	v_exp_f32_e32 v16, v16
	v_exp_f32_e32 v25, v25
	v_fma_f32 v35, -v34, v34, 1.0
	v_sqrt_f32_e32 v35, v35
	v_add_f32_e32 v16, 1.0, v16
	v_add_f32_e32 v21, 1.0, v25
	v_rcp_f32_e32 v16, v16
	v_rcp_f32_e32 v25, v21
	v_fma_f32 v21, -v40, v40, 1.0
	v_sqrt_f32_e32 v41, v21
	v_fmamk_f32 v21, v26, 0xbfb8aa3b, v93
	v_mul_f32_e32 v16, v16, v33
	v_exp_f32_e32 v26, v21
	v_mul_f32_e32 v21, v8, v17
	v_mul_f32_e32 v8, v25, v41
	v_exp_f32_e32 v41, v16
	v_fmamk_f32 v16, v43, 0xbfb8aa3b, v151
	v_exp_f32_e32 v16, v16
	v_add_f32_e32 v17, 1.0, v26
	v_fma_f32 v25, -v41, v41, 1.0
	v_fmamk_f32 v26, v27, 0xbfb8aa3b, v93
	v_add_f32_e32 v16, 1.0, v16
	v_rcp_f32_e32 v16, v16
	v_rcp_f32_e32 v17, v17
	v_sqrt_f32_e32 v25, v25
	v_mul_f32_e32 v16, v16, v33
	v_exp_f32_e32 v26, v26
	v_exp_f32_e32 v153, v16
	v_mul_f32_e32 v154, v17, v25
	v_fmamk_f32 v25, v44, 0xbfb8aa3b, v151
	v_add_f32_e32 v16, 1.0, v26
	v_fmamk_f32 v26, v28, 0xbfb8aa3b, v93
	v_fma_f32 v17, -v153, v153, 1.0
	v_exp_f32_e32 v25, v25
	v_rcp_f32_e32 v16, v16
	v_sqrt_f32_e32 v17, v17
	v_exp_f32_e32 v26, v26
	v_add_f32_e32 v25, 1.0, v25
	v_rcp_f32_e32 v25, v25
	v_mul_f32_e32 v155, v16, v17
	v_add_f32_e32 v16, 1.0, v26
	v_fmamk_f32 v26, v29, 0xbfb8aa3b, v93
	v_exp_f32_e32 v26, v26
	v_rcp_f32_e32 v17, v16
	v_mul_f32_e32 v16, v25, v33
	v_fmamk_f32 v25, v45, 0xbfb8aa3b, v151
	v_exp_f32_e32 v25, v25
	v_add_f32_e32 v26, 1.0, v26
	v_rcp_f32_e32 v42, v26
	v_fmamk_f32 v26, v46, 0xbfb8aa3b, v151
	v_exp_f32_e32 v26, v26
	v_add_f32_e32 v25, 1.0, v25
	v_rcp_f32_e32 v25, v25
	v_fmamk_f32 v27, v30, 0xbfb8aa3b, v93
	v_exp_f32_e32 v27, v27
	v_add_f32_e32 v26, 1.0, v26
	v_rcp_f32_e32 v26, v26
	v_mul_f32_e32 v25, v25, v33
	v_exp_f32_e32 v43, v25
	v_add_f32_e32 v25, 1.0, v27
	v_rcp_f32_e32 v44, v25
	v_mul_f32_e32 v25, v26, v33
	v_fmamk_f32 v26, v47, 0xbfb8aa3b, v151
	v_exp_f32_e32 v26, v26
	v_fmamk_f32 v27, v31, 0xbfb8aa3b, v93
	v_exp_f32_e32 v27, v27
	v_add_f32_e32 v26, 1.0, v26
	v_rcp_f32_e32 v26, v26
	v_exp_f32_e32 v16, v16
	v_fmac_f32_e32 v18, 0, v32
	v_mul_f32_e32 v35, v166, v35
	v_exp_f32_e32 v45, v25
	v_add_f32_e32 v25, 1.0, v27
	v_mul_f32_e32 v31, v34, v18
	v_rcp_f32_e32 v46, v25
	v_mul_f32_e32 v25, v26, v33
	v_fmac_f32_e32 v31, v1, v35
	v_mul_f32_e32 v33, v32, v34
	v_fmac_f32_e32 v19, 0, v20
	v_mul_f32_e32 v30, v0, v31
	v_mul_f32_e32 v34, v0, v33
	v_mul_f32_e32 v28, v37, v19
	v_fma_f32 v0, -v16, v16, 1.0
	v_fmac_f32_e32 v28, v5, v4
	v_sqrt_f32_e32 v1, v0
	v_mul_f32_e32 v27, v38, v28
	v_fmac_f32_e32 v30, v2, v91
	v_fmac_f32_e32 v27, v6, v23
	v_fma_f32 v2, -v43, v43, 1.0
	v_mul_f32_e32 v26, v39, v27
	v_mov_b32_e32 v0, v89
	v_sqrt_f32_e32 v2, v2
	v_fmac_f32_e32 v26, v7, v24
	v_pk_mul_f32 v[6:7], v[16:17], v[0:1]
	v_mul_f32_e32 v29, v152, v30
	v_fmac_f32_e32 v6, v12, v7
	v_fmac_f32_e32 v29, v3, v36
	v_mov_b32_e32 v3, v6
	v_pk_mul_f32 v[4:5], v[42:43], v[2:3]
	v_fma_f32 v0, -v45, v45, 1.0
	v_exp_f32_e32 v47, v25
	v_fmac_f32_e32 v5, v13, v4
	v_sqrt_f32_e32 v4, v0
	v_fmac_f32_e32 v21, 0, v22
	v_mul_f32_e32 v25, v40, v21
	v_fmac_f32_e32 v25, v9, v8
	v_pk_mul_f32 v[8:9], v[44:45], v[4:5]
	v_fma_f32 v0, -v47, v47, 1.0
	v_fmac_f32_e32 v9, v14, v8
	v_sqrt_f32_e32 v8, v0
	ds_bpermute_b32 v0, v140, v29
	v_mul_f32_e32 v24, v41, v25
	v_mul_f32_e32 v35, v152, v34
	v_mul_f32_e32 v36, v20, v37
	v_fmac_f32_e32 v24, v10, v154
	v_mul_f32_e32 v37, v38, v36
	v_mul_f32_e32 v23, v153, v24
	ds_bpermute_b32 v13, v140, v35
	v_mul_f32_e32 v38, v39, v37
	v_fmac_f32_e32 v23, v11, v155
	v_pk_mul_f32 v[10:11], v[46:47], v[8:9]
	s_waitcnt lgkmcnt(1)
	v_cndmask_b32_e64 v14, v29, v0, s[0:1]
	v_fmac_f32_e32 v11, v15, v10
	v_cndmask_b32_e64 v10, v0, v29, s[0:1]
	ds_bpermute_b32 v0, v140, v38
	ds_bpermute_b32 v3, v140, v26
	v_mul_f32_e32 v39, v22, v40
	v_mul_f32_e32 v40, v41, v39
	s_waitcnt lgkmcnt(2)
	v_cndmask_b32_e64 v1, v13, v35, s[0:1]
	v_mul_f32_e32 v12, v153, v40
	v_mul_f32_e32 v7, v16, v43
	v_cndmask_b32_e64 v2, v35, v13, s[0:1]
	v_fmac_f32_e32 v10, 0, v1
	v_mul_f32_e32 v4, v45, v7
	v_mul_f32_e32 v15, v35, v13
	v_fmac_f32_e32 v14, v2, v10
	s_waitcnt lgkmcnt(1)
	v_cndmask_b32_e64 v1, v0, v38, s[0:1]
	s_waitcnt lgkmcnt(0)
	v_cndmask_b32_e64 v17, v3, v26, s[0:1]
	v_cndmask_b32_e64 v41, v26, v3, s[0:1]
	ds_bpermute_b32 v2, v140, v12
	ds_bpermute_b32 v3, v140, v23
	v_mul_f32_e32 v8, v47, v4
	v_cndmask_b32_e64 v0, v38, v0, s[0:1]
	v_mul_f32_e32 v42, v15, v1
	v_fmac_f32_e32 v17, v1, v14
	v_mul_f32_e32 v43, v0, v42
	v_fmac_f32_e32 v41, v0, v17
	ds_bpermute_b32 v1, v140, v8
	ds_bpermute_b32 v0, v140, v11
	s_waitcnt lgkmcnt(3)
	v_cndmask_b32_e64 v47, v2, v12, s[0:1]
	s_waitcnt lgkmcnt(2)
	v_cndmask_b32_e64 v44, v3, v23, s[0:1]
	v_cndmask_b32_e64 v2, v12, v2, s[0:1]
	v_cndmask_b32_e64 v45, v23, v3, s[0:1]
	v_mul_f32_e32 v46, v47, v43
	v_fmac_f32_e32 v44, v47, v41
	v_mul_f32_e32 v47, v2, v46
	v_fmac_f32_e32 v45, v2, v44
	s_waitcnt lgkmcnt(1)
	v_cndmask_b32_e64 v2, v1, v8, s[0:1]
	s_waitcnt lgkmcnt(0)
	v_cndmask_b32_e64 v91, v0, v11, s[0:1]
	v_mul_f32_e32 v93, v2, v47
	v_fmac_f32_e32 v91, v2, v45
	s_and_saveexec_b64 s[6:7], s[0:1]
	v_mul_f32_e32 v3, v91, v1
	v_mul_f32_e32 v2, v93, v1
	v_add_f32_e32 v3, v3, v0
	ds_write_b64 v139, v[2:3] offset:2048
	s_or_b64 exec, exec, s[6:7]
	v_cndmask_b32_e64 v0, 0, 1, s[12:13]
	v_cmp_ne_u32_e64 s[6:7], 1, v0
	s_andn2_b64 vcc, exec, s[12:13]
	s_waitcnt lgkmcnt(0)
	s_barrier
	s_cbranch_vccnz .LBB0_340
	s_cmp_lt_u32 s62, 8
	s_cbranch_scc1 .LBB0_341
	s_add_i32 s9, 16, 0x800
	s_and_b32 s8, s62, 0x7ffffff8
	v_add3_u32 v151, v141, v138, s9
	v_mov_b32_e32 v0, 1.0
	v_mov_b32_e32 v3, 0
	s_mov_b32 s9, 0
